# band attention: K/V tile prefetch two tiles ahead (second register set, parity-selected LDS write and load, counted vmcnt wait)
# speedup vs baseline: 1.0030x; 1.0030x over previous
.LBB0_450:
	s_or_b64 exec, exec, s[26:27]
	s_ashr_i32 s23, s23, 8
	s_lshl_b32 s62, s23, 2
	s_add_i32 s23, s62, -8
	s_cmpk_gt_i32 s92, 0x2ff
	s_cselect_b32 s23, s23, 0
	s_or_b32 s24, s62, 3
	s_cmp_le_i32 s23, s24
	s_cbranch_scc0 .LBB0_465
	s_lshl_b32 s60, s23, 6
	s_add_i32 s60, s60, s93
	v_add_u32_e32 v4, s60, v150
	v_ashrrev_i32_e32 v5, 31, v4
	v_lshlrev_b64 v[4:5], 11, v[4:5]
	s_lshl_b64 s[26:27], s[16:17], 1
	v_lshl_add_u64 v[6:7], s[50:51], 0, v[4:5]
	v_lshl_add_u64 v[4:5], s[48:49], 0, v[4:5]
	v_lshl_add_u64 v[6:7], v[6:7], 0, s[26:27]
	v_lshl_add_u64 v[4:5], v[4:5], 0, s[26:27]
	v_lshl_add_u64 v[6:7], v[6:7], 0, v[108:109]
	v_lshl_add_u64 v[4:5], v[4:5], 0, v[108:109]
	s_add_i32 s62, s62, s29
	v_mov_b32_e32 v16, v3
	v_mov_b32_e32 v17, v3
	s_sub_i32 s64, s62, s23
	v_mov_b32_e32 v2, v3
	v_mov_b32_e32 v4, v3
	v_mov_b32_e32 v5, v3
	v_mov_b32_e32 v6, v3
	v_mov_b32_e32 v7, v3
	v_mov_b32_e32 v8, v3
	v_mov_b32_e32 v9, v3
	v_mov_b32_e32 v10, v3
	v_mov_b32_e32 v11, v3
	v_mov_b32_e32 v12, v3
	v_mov_b32_e32 v13, v3
	v_mov_b32_e32 v14, v3
	v_mov_b32_e32 v15, v3
	v_mov_b64_e32 v[48:49], v[16:17]
	v_mov_b64_e32 v[32:33], v[16:17]
	v_lshl_add_u64 v[124:125], v[110:111], 0, s[26:27]
	v_lshl_add_u64 v[126:127], v[112:113], 0, s[26:27]
	s_add_i32 s63, s62, -8
	v_lshl_add_u32 v119, s64, 6, v162
	v_add_u32_e32 v128, s60, v163
	v_mov_b32_e32 v173, 0xf149f2ca
	v_mov_b32_e32 v172, 0
	v_mov_b64_e32 v[46:47], v[14:15]
	v_mov_b64_e32 v[44:45], v[12:13]
	v_mov_b64_e32 v[42:43], v[10:11]
	v_mov_b64_e32 v[40:41], v[8:9]
	v_mov_b64_e32 v[38:39], v[6:7]
	v_mov_b64_e32 v[36:37], v[4:5]
	v_mov_b64_e32 v[34:35], v[2:3]
	v_mov_b64_e32 v[30:31], v[14:15]
	v_mov_b64_e32 v[28:29], v[12:13]
	v_mov_b64_e32 v[26:27], v[10:11]
	v_mov_b64_e32 v[24:25], v[8:9]
	v_mov_b64_e32 v[22:23], v[6:7]
	v_mov_b64_e32 v[20:21], v[4:5]
	v_mov_b64_e32 v[18:19], v[2:3]
	s_mov_b32 s99, 0
	v_ashrrev_i32_e32 v129, 31, v128
	v_lshlrev_b64 v[4:5], 11, v[128:129]
	v_lshl_add_u64 v[6:7], v[126:127], 0, v[4:5]
	v_lshl_add_u64 v[4:5], v[124:125], 0, v[4:5]
	global_load_dwordx4 v[186:189], v[4:5], off
	global_load_dwordx4 v[190:193], v[6:7], off
	v_add_u32_e32 v128, 64, v128
.LBB0_452:
	s_cmp_ge_i32 s23, s24
	s_cselect_b64 s[26:27], -1, 0
	v_add_u32_e32 v2, v114, v151
	s_waitcnt lgkmcnt(0)
	s_barrier
	s_and_b64 vcc, exec, s[26:27]
	s_cbranch_vccnz .Lbp_w0
	s_waitcnt vmcnt(2)
	s_branch .Lbp_w1

.Lbp_w1:
	s_cmp_eq_u32 s99, 0
	s_cbranch_scc0 .Lbp_wB
	ds_write_b128 v2, v[102:105]
	ds_write_b128 v164, v[98:101] offset:9216
	s_branch .Lbp_wd
.Lbp_wB:
	ds_write_b128 v2, v[186:189]
	ds_write_b128 v164, v[190:193] offset:9216
.Lbp_wd:
	s_waitcnt lgkmcnt(0)
	s_barrier
	s_add_i32 s98, s23, 1
	s_cmp_ge_i32 s98, s24
	s_cbranch_scc1 .LBB0_454
	v_ashrrev_i32_e32 v129, 31, v128
	v_lshlrev_b64 v[4:5], 11, v[128:129]
	v_lshl_add_u64 v[6:7], v[126:127], 0, v[4:5]
	v_lshl_add_u64 v[4:5], v[124:125], 0, v[4:5]
	s_cmp_eq_u32 s99, 0
	s_cbranch_scc0 .Lbp_lB
	global_load_dwordx4 v[102:105], v[4:5], off
	global_load_dwordx4 v[98:101], v[6:7], off
	s_branch .LBB0_454
.Lbp_lB:
	global_load_dwordx4 v[186:189], v[4:5], off
	global_load_dwordx4 v[190:193], v[6:7], off

.LBB0_463:
	s_xor_b32 s99, s99, 1
	s_add_i32 s23, s23, 1
	v_subrev_u32_e32 v119, 64, v119
	s_add_i32 s64, s64, -1
	v_add_u32_e32 v128, 64, v128
	s_and_b64 vcc, exec, s[26:27]
	s_cbranch_vccnz .LBB0_466
	v_mov_b32_e32 v173, v50
	s_branch .LBB0_452
